# static s_setprio 1 for the younger wave half during the SCAN phase (reset at the grid barrier)
# baseline (speedup 1.0000x reference)
; #define LAS __attribute__((address_space(3)))
; __device__ __forceinline__ void scan_prompt_unit(const Ctx& c, int b, int h) {
;     LAS unsigned char* lds = c.lds;
;     const int tid = c.tid, lane = c.lane, w = c.wave, q = lane >> 4, c16 = lane & 15, g = h >> 3;
; __device__ __forceinline__ void scan_phase(const Ctx& c, int mode) {
;     if (mode != 2) for (int u = c.bid; u < 256; u += c.G) scan_prompt_unit(c, u >> 5, u & 31);
.Lscan_perm1:
	s_cmp_lt_u32 s92, 4
	s_cbranch_scc1 .Lscan_noprio
	s_setprio 1

; __global__ void __launch_bounds__(512, 2) hybrid_fwd(Args args) {
;     ...
;         if (st + 1 < NSTEPS) { if (st == 0) grid.sync(); else xcd_barrier(xbar); }
.LBB0_949:
	s_and_b64 vcc, exec, s[2:3]
	s_cbranch_vccz .LBB0_1003
	s_setprio 0
	s_waitcnt vmcnt(0) lgkmcnt(0)
	s_barrier
	s_mov_b64 s[2:3], exec
	v_readlane_b32 s4, v253, 45
	v_readlane_b32 s5, v253, 46
	s_and_b64 s[4:5], s[2:3], s[4:5]
	s_mov_b64 exec, s[4:5]
	s_cbranch_execz .LBB0_960
	buffer_wbl2 sc1
	s_load_dwordx2 s[4:5], s[94:95], 0x58
	s_mov_b64 s[6:7], exec
	v_mbcnt_lo_u32_b32 v1, s6, 0
	v_mbcnt_hi_u32_b32 v1, s7, v1
	v_cmp_eq_u32_e32 vcc, 0, v1
	s_waitcnt lgkmcnt(0)
	global_load_dword v0, v2, s[4:5] offset:40
	s_and_saveexec_b64 s[8:9], vcc
	s_cbranch_execz .LBB0_953
	s_bcnt1_i32_b64 s6, s[6:7]
	v_mov_b32_e32 v3, s6
	global_atomic_add v3, v2, v3, s[4:5] offset:32 sc0
